# FFN rms-norm row loop: next row's lines touched (loads into unused registers) right after the hoisted modulation loads (on top of v41)
# speedup vs baseline: 1.0046x; 1.0046x over previous
.LBB0_1101:
	s_waitcnt vmcnt(3)
	v_mul_f32_e32 v0, v31, v31
	s_waitcnt vmcnt(2)
	v_mul_f32_e32 v40, v27, v27
	v_fmac_f32_e32 v0, v30, v30
	v_fmac_f32_e32 v40, v26, v26
	v_fmac_f32_e32 v0, v32, v32
	v_fmac_f32_e32 v40, v28, v28
	v_fmac_f32_e32 v0, v33, v33
	v_fmac_f32_e32 v40, v29, v29
	s_waitcnt vmcnt(0)
	v_pk_mul_f32 v[54:55], v[18:19], v[18:19]
	v_pk_mul_f32 v[56:57], v[22:23], v[22:23]
	v_add_f32_e32 v0, v0, v40
	v_pk_mul_f32 v[40:41], v[20:21], v[20:21]
	v_pk_mul_f32 v[52:53], v[24:25], v[24:25]
	v_mov_b32_e32 v58, v54
	v_mov_b32_e32 v59, v56
	v_mov_b32_e32 v56, v55
	v_pk_add_f32 v[54:55], v[58:59], v[56:57]
	v_mov_b32_e32 v56, v40
	v_mov_b32_e32 v57, v52
	v_pk_add_f32 v[54:55], v[56:57], v[54:55]
	v_mov_b32_e32 v52, v41
	v_pk_add_f32 v[40:41], v[52:53], v[54:55]
	s_cmpk_lt_u32 s6, 0x4000
	v_add_f32_e32 v0, v41, v0
	v_add_f32_e32 v0, v40, v0
	ds_bpermute_b32 v40, v42, v0
	s_movk_i32 s5, 0x4800
	s_cselect_b32 s5, 0x2400, s5
	s_cmpk_gt_i32 s6, 0x1fff
	s_cselect_b32 s5, s5, 0
	s_waitcnt lgkmcnt(0)
	v_add_f32_e32 v0, v0, v40
	ds_bpermute_b32 v40, v43, v0
	s_lshl_b32 s5, s5, 2
	s_add_u32 s8, s0, s5
	s_addc_u32 s9, s1, 0
	s_add_u32 s10, s8, 0x1000
	s_waitcnt lgkmcnt(0)
	v_add_f32_e32 v0, v0, v40
	ds_bpermute_b32 v40, v44, v0
	s_addc_u32 s11, s9, 0
	global_load_dwordx4 v[60:63], v48, s[10:11]
	global_load_dwordx4 v[64:67], v48, s[8:9]
	global_load_dwordx4 v[68:71], v49, s[10:11]
	global_load_dwordx4 v[72:75], v48, s[8:9] offset:1024
	global_load_dwordx4 v[76:79], v50, s[10:11]
	global_load_dwordx4 v[80:83], v48, s[8:9] offset:2048
	global_load_dwordx4 v[84:87], v51, s[10:11]
	global_load_dwordx4 v[88:91], v48, s[8:9] offset:3072
	v_readlane_b32 s36, v249, 52
	s_add_i32 s36, s6, s36
	s_cmp_ge_i32 s36, s12
	s_cbranch_scc1 .Lnf_selftouch
	s_add_i32 s37, s36, 0xffffc000
	s_cmpk_lt_i32 s36, 0x4000
	s_cselect_b32 s38, s36, s37
	s_cselect_b32 s27, s79, s97
	s_cselect_b32 s26, s78, s96
	s_ashr_i32 s39, s38, 31
	s_lshl_b64 s[38:39], s[38:39], 12
	s_add_u32 s26, s26, s38
	s_addc_u32 s27, s27, s39
	s_branch .Lnf_touch
.Lnf_selftouch:
	s_mov_b64 s[26:27], s[8:9]
.Lnf_touch:
	global_load_dwordx4 v[92:95], v48, s[26:27]
	global_load_dwordx4 v[92:95], v48, s[26:27] offset:1024
	global_load_dwordx4 v[92:95], v48, s[26:27] offset:2048
	global_load_dwordx4 v[92:95], v48, s[26:27] offset:3072
	s_waitcnt lgkmcnt(0)
	v_add_f32_e32 v0, v0, v40
	ds_bpermute_b32 v40, v45, v0
	s_waitcnt lgkmcnt(0)
	v_add_f32_e32 v0, v0, v40
	ds_bpermute_b32 v40, v46, v0
	s_waitcnt lgkmcnt(0)
	v_add_f32_e32 v0, v0, v40
	ds_bpermute_b32 v40, v47, v0
	s_waitcnt lgkmcnt(0)
	v_add_f32_e32 v0, v0, v40
	v_fmamk_f32 v0, v0, 0x3a800000, v199
	v_cmp_gt_f32_e32 vcc, s21, v0
	v_mul_f32_e32 v40, 0x4f800000, v0
	s_nop 0
	v_cndmask_b32_e32 v0, v0, v40, vcc
	v_sqrt_f32_e32 v40, v0
	s_nop 0
	v_add_u32_e32 v41, -1, v40
	v_fma_f32 v52, -v41, v40, v0
	v_cmp_ge_f32_e64 s[38:39], 0, v52
	v_add_u32_e32 v52, 1, v40
	s_nop 0
	v_cndmask_b32_e64 v41, v40, v41, s[38:39]
	v_fma_f32 v40, -v52, v40, v0
	v_cmp_lt_f32_e64 s[38:39], 0, v40
	s_nop 1
	v_cndmask_b32_e64 v40, v41, v52, s[38:39]
	v_mul_f32_e32 v41, 0x37800000, v40
	v_cndmask_b32_e32 v40, v40, v41, vcc
	v_cmp_class_f32_e32 vcc, v0, v200
	s_nop 1
	v_cndmask_b32_e32 v0, v40, v0, vcc
	v_div_scale_f32 v40, s[16:17], v0, v0, 1.0
	v_rcp_f32_e32 v41, v40
	s_lshl_b64 s[16:17], s[6:7], 11
	v_fma_f32 v52, -v40, v41, 1.0
	v_fmac_f32_e32 v41, v52, v41
	v_div_scale_f32 v52, vcc, 1.0, v0, 1.0
	v_mul_f32_e32 v53, v52, v41
	v_fma_f32 v54, -v40, v53, v52
	v_fmac_f32_e32 v53, v54, v41
	v_fma_f32 v40, -v40, v53, v52
	v_div_fmas_f32 v40, v40, v41, v53
	v_div_fixup_f32 v0, v40, v0, 1.0
	v_pk_mul_f32 v[30:31], v[30:31], v[0:1] op_sel_hi:[1,0]
	v_pk_mul_f32 v[32:33], v[32:33], v[0:1] op_sel_hi:[1,0]
	v_pk_mul_f32 v[30:31], v[2:3], v[30:31]
	v_pk_mul_f32 v[32:33], v[4:5], v[32:33]
	v_pk_mul_f32 v[26:27], v[26:27], v[0:1] op_sel_hi:[1,0]
	v_pk_mul_f32 v[28:29], v[28:29], v[0:1] op_sel_hi:[1,0]
	v_pk_mul_f32 v[26:27], v[6:7], v[26:27]
	v_pk_mul_f32 v[28:29], v[8:9], v[28:29]
	v_pk_mul_f32 v[22:23], v[22:23], v[0:1] op_sel_hi:[1,0]
	v_pk_mul_f32 v[24:25], v[24:25], v[0:1] op_sel_hi:[1,0]
	v_pk_mul_f32 v[22:23], v[10:11], v[22:23]
	v_pk_mul_f32 v[24:25], v[12:13], v[24:25]
	v_pk_mul_f32 v[18:19], v[18:19], v[0:1] op_sel_hi:[1,0]
	v_pk_mul_f32 v[20:21], v[20:21], v[0:1] op_sel_hi:[1,0]
	v_pk_mul_f32 v[18:19], v[18:19], v[14:15]
	v_pk_mul_f32 v[20:21], v[20:21], v[16:17]
	s_waitcnt vmcnt(4)
	v_pk_add_f32 v[40:41], v[60:61], 1.0 op_sel_hi:[1,0]
	s_nop 0
	v_pk_fma_f32 v[30:31], v[40:41], v[30:31], v[64:65]
	v_pk_add_f32 v[40:41], v[62:63], 1.0 op_sel_hi:[1,0]
	s_nop 0
	v_pk_fma_f32 v[32:33], v[40:41], v[32:33], v[66:67]
	v_cvt_pk_bf16_f32 v40, v30, v31
	v_cvt_pk_bf16_f32 v41, v32, v33
	v_lshl_add_u64 v[30:31], v[36:37], 0, s[16:17]
	global_store_dwordx2 v[30:31], v[40:41], off
	v_pk_add_f32 v[32:33], v[68:69], 1.0 op_sel_hi:[1,0]
	s_nop 0
	v_pk_fma_f32 v[26:27], v[32:33], v[26:27], v[72:73]
	v_pk_add_f32 v[32:33], v[70:71], 1.0 op_sel_hi:[1,0]
	v_cvt_pk_bf16_f32 v26, v26, v27
	v_pk_fma_f32 v[28:29], v[32:33], v[28:29], v[74:75]
	s_nop 0
	v_cvt_pk_bf16_f32 v27, v28, v29
	global_store_dwordx2 v[30:31], v[26:27], off offset:512
	v_pk_add_f32 v[26:27], v[76:77], 1.0 op_sel_hi:[1,0]
	s_nop 0
	v_pk_fma_f32 v[22:23], v[22:23], v[26:27], v[80:81]
	v_pk_add_f32 v[26:27], v[78:79], 1.0 op_sel_hi:[1,0]
	v_cvt_pk_bf16_f32 v22, v22, v23
	v_pk_fma_f32 v[24:25], v[24:25], v[26:27], v[82:83]
	s_nop 0
	v_cvt_pk_bf16_f32 v23, v24, v25
	global_store_dwordx2 v[30:31], v[22:23], off offset:1024
	v_readlane_b32 s8, v249, 52
	s_add_i32 s6, s6, s8
	s_add_i32 s4, s4, s8
	s_cmp_ge_i32 s6, s12
	v_readlane_b32 s9, v249, 53
	v_pk_add_f32 v[26:27], v[84:85], 1.0 op_sel_hi:[1,0]
	s_nop 0
	v_pk_fma_f32 v[18:19], v[18:19], v[26:27], v[88:89]
	v_pk_add_f32 v[22:23], v[86:87], 1.0 op_sel_hi:[1,0]
	v_cvt_pk_bf16_f32 v18, v18, v19
	v_pk_fma_f32 v[20:21], v[20:21], v[22:23], v[90:91]
	s_nop 0
	v_cvt_pk_bf16_f32 v19, v20, v21
	global_store_dwordx2 v[30:31], v[18:19], off offset:1536
	s_cbranch_scc1 .LBB0_1106
